# attention K/V staging: per-tile address recomputation replaced by recorded per-lane addresses advanced by a constant stride (first in-loop tile keeps the original code); no numeric change
# speedup vs baseline: 1.0201x; 1.0201x over previous
.LBB0_835:
	s_waitcnt vmcnt(0)
	s_add_i32 s88, s34, 1
	s_cmp_ge_u32 s88, s87
	s_waitcnt lgkmcnt(0)
	s_barrier
	s_cbranch_scc1 .LBB0_881
	s_lshl_b32 s89, s88, 6
	s_add_u32 s28, s56, s89
	s_addc_u32 s29, s57, 0
	s_bitcmp1_b32 s88, 0
	s_cselect_b32 s35, 0x5800, 0
	s_cmp_lg_u32 s88, 1
	s_cbranch_scc1 .Lhwat0_fast
	s_and_saveexec_b64 s[66:67], s[4:5]
	s_cbranch_execnz .LBB0_840
	s_or_b64 exec, exec, s[66:67]
	s_and_saveexec_b64 s[66:67], s[6:7]
	s_cbranch_execnz .LBB0_849

.LBB0_846:
	s_andn2_saveexec_b64 s[68:69], s[68:69]
	v_lshlrev_b64 v[64:65], 10, v[66:67]
	v_lshl_add_u64 v[64:65], v[156:157], 0, v[64:65]
	s_or_b64 exec, exec, s[68:69]
	v_mov_b32_e32 v152, v64
	v_mov_b32_e32 v153, v65
	s_andn2_b64 vcc, s[12:13], s[14:15]
	v_mov_b32_e32 v154, 0x10000
	v_mov_b32_e32 v67, 0x1000
	v_cndmask_b32_e32 v154, v154, v67, vcc
	v_readfirstlane_b32 s98, v191
	v_add_u32_e32 v66, s35, v191
	s_nop 0
	v_readfirstlane_b32 s30, v66
	s_mov_b32 m0, s30
	s_nop 0
	global_load_lds_dwordx4 v[64:65], off
	s_or_b64 exec, exec, s[66:67]
	s_and_saveexec_b64 s[66:67], s[6:7]
	s_cbranch_execz .LBB0_838

.LBB0_855:
	s_andn2_saveexec_b64 s[68:69], s[68:69]
	v_lshlrev_b64 v[64:65], 10, v[66:67]
	v_lshl_add_u64 v[64:65], v[162:163], 0, v[64:65]
	s_or_b64 exec, exec, s[68:69]
	v_mov_b32_e32 v158, v64
	v_mov_b32_e32 v159, v65
	s_andn2_b64 vcc, s[16:17], s[18:19]
	v_mov_b32_e32 v160, 0x10000
	v_mov_b32_e32 v67, 0x1000
	v_cndmask_b32_e32 v160, v160, v67, vcc
	v_readfirstlane_b32 s99, v196
	v_add_u32_e32 v66, s35, v196
	s_nop 0
	v_readfirstlane_b32 s30, v66
	s_mov_b32 m0, s30
	s_nop 0
	global_load_lds_dwordx4 v[64:65], off
	s_or_b64 exec, exec, s[66:67]
	s_and_saveexec_b64 s[66:67], s[8:9]
	s_cbranch_execz .LBB0_839

.LBB0_864:
	s_andn2_saveexec_b64 s[68:69], s[68:69]
	v_lshlrev_b64 v[64:65], 10, v[66:67]
	v_lshl_add_u64 v[64:65], v[168:169], 0, v[64:65]
	s_or_b64 exec, exec, s[68:69]
	v_mov_b32_e32 v164, v64
	v_mov_b32_e32 v165, v65
	s_andn2_b64 vcc, s[20:21], s[22:23]
	v_mov_b32_e32 v166, 0x10000
	v_mov_b32_e32 v67, 0x1000
	v_cndmask_b32_e32 v166, v166, v67, vcc
	v_readfirstlane_b32 s100, v189
	v_add_u32_e32 v66, s35, v189
	s_nop 0
	v_readfirstlane_b32 s30, v66
	s_mov_b32 m0, s30
	s_nop 0
	global_load_lds_dwordx4 v[64:65], off
	s_or_b64 exec, exec, s[66:67]
	s_and_saveexec_b64 s[66:67], s[10:11]
	s_cbranch_execz .LBB0_876

.LBB0_873:
	s_andn2_saveexec_b64 s[28:29], s[28:29]
	v_lshlrev_b64 v[64:65], 10, v[66:67]
	v_lshl_add_u64 v[64:65], v[174:175], 0, v[64:65]
	s_or_b64 exec, exec, s[28:29]
	v_mov_b32_e32 v170, v64
	v_mov_b32_e32 v171, v65
	s_andn2_b64 vcc, s[24:25], s[26:27]
	v_mov_b32_e32 v172, 0x10000
	v_mov_b32_e32 v67, 0x1000
	v_cndmask_b32_e32 v172, v172, v67, vcc
	v_readfirstlane_b32 s101, v197
	v_add_u32_e32 v66, s35, v197
	s_nop 0
	v_readfirstlane_b32 s28, v66
	s_mov_b32 m0, s28
	s_nop 0
	global_load_lds_dwordx4 v[64:65], off

.LBB0_879:
	v_add_u32_e32 v64, s35, v189
	v_add_u32_e32 v66, 0x3400, v64
	v_lshl_add_u64 v[64:65], v[148:149], 1, s[28:29]
	v_readfirstlane_b32 s28, v66
	v_lshl_add_u64 v[64:65], v[184:185], 1, v[64:65]
	v_mov_b32_e32 v148, v64
	v_mov_b32_e32 v149, v65
	s_mov_b32 m0, s28
	s_nop 0
	global_load_lds_dwordx4 v[64:65], off
.LBB0_880:
	s_or_b64 exec, exec, s[66:67]
	s_branch .LBB0_881
.Lhwat0_fast:
	s_and_saveexec_b64 s[66:67], s[4:5]
	s_cbranch_execz .Lhwat0_k0
	s_add_u32 m0, s98, s35
	v_add_co_u32_e32 v152, vcc, v152, v154
	s_nop 1
	v_addc_co_u32_e32 v153, vcc, 0, v153, vcc
	global_load_lds_dwordx4 v[152:153], off
.Lhwat0_k0:
	s_or_b64 exec, exec, s[66:67]
	s_and_saveexec_b64 s[66:67], s[6:7]
	s_cbranch_execz .Lhwat0_k1
	s_add_u32 m0, s99, s35
	v_add_co_u32_e32 v158, vcc, v158, v160
	s_nop 1
	v_addc_co_u32_e32 v159, vcc, 0, v159, vcc
	global_load_lds_dwordx4 v[158:159], off
.Lhwat0_k1:
	s_or_b64 exec, exec, s[66:67]
	s_and_saveexec_b64 s[66:67], s[8:9]
	s_cbranch_execz .Lhwat0_k2
	s_add_u32 m0, s100, s35
	v_add_co_u32_e32 v164, vcc, v164, v166
	s_nop 1
	v_addc_co_u32_e32 v165, vcc, 0, v165, vcc
	global_load_lds_dwordx4 v[164:165], off
.Lhwat0_k2:
	s_or_b64 exec, exec, s[66:67]
	s_and_saveexec_b64 s[66:67], s[10:11]
	s_cbranch_execz .Lhwat0_k3
	s_add_u32 m0, s101, s35
	v_add_co_u32_e32 v170, vcc, v170, v172
	s_nop 1
	v_addc_co_u32_e32 v171, vcc, 0, v171, vcc
	global_load_lds_dwordx4 v[170:171], off
.Lhwat0_k3:
	s_or_b64 exec, exec, s[66:67]
	s_and_saveexec_b64 s[66:67], s[6:7]
	s_cbranch_execz .Lhwat0_v0
	s_add_u32 s30, s98, s35
	s_add_u32 m0, s30, 0x3400
	v_add_co_u32_e32 v176, vcc, 0x80, v176
	s_nop 1
	v_addc_co_u32_e32 v177, vcc, 0, v177, vcc
	global_load_lds_dwordx4 v[176:177], off
.Lhwat0_v0:
	s_or_b64 exec, exec, s[66:67]
	s_and_saveexec_b64 s[66:67], s[8:9]
	s_cbranch_execz .Lhwat0_v1
	s_add_u32 s30, s99, s35
	s_add_u32 m0, s30, 0x3400
	v_add_co_u32_e32 v180, vcc, 0x80, v180
	s_nop 1
	v_addc_co_u32_e32 v181, vcc, 0, v181, vcc
	global_load_lds_dwordx4 v[180:181], off
.Lhwat0_v1:
	s_or_b64 exec, exec, s[66:67]
	s_and_saveexec_b64 s[66:67], s[10:11]
	s_cbranch_execz .Lhwat0_v2
	s_add_u32 s30, s100, s35
	s_add_u32 m0, s30, 0x3400
	v_add_co_u32_e32 v148, vcc, 0x80, v148
	s_nop 1
	v_addc_co_u32_e32 v149, vcc, 0, v149, vcc
	global_load_lds_dwordx4 v[148:149], off

.LBB0_891:
	v_add_u32_e32 v64, s35, v191
	v_add_u32_e32 v66, 0x3400, v64
	v_lshl_add_u64 v[64:65], v[176:177], 1, s[28:29]
	v_readfirstlane_b32 s30, v66
	v_lshl_add_u64 v[64:65], v[178:179], 1, v[64:65]
	v_mov_b32_e32 v176, v64
	v_mov_b32_e32 v177, v65
	s_mov_b32 m0, s30
	s_nop 0
	global_load_lds_dwordx4 v[64:65], off
	s_or_b64 exec, exec, s[66:67]
	s_and_saveexec_b64 s[66:67], s[8:9]
	s_cbranch_execz .LBB0_878
.LBB0_892:
	v_add_u32_e32 v64, s35, v196
	v_add_u32_e32 v66, 0x3400, v64
	v_lshl_add_u64 v[64:65], v[180:181], 1, s[28:29]
	v_readfirstlane_b32 s30, v66
	v_lshl_add_u64 v[64:65], v[182:183], 1, v[64:65]
	v_mov_b32_e32 v180, v64
	v_mov_b32_e32 v181, v65
	s_mov_b32 m0, s30
	s_nop 0
	global_load_lds_dwordx4 v[64:65], off
	s_or_b64 exec, exec, s[66:67]
	s_and_saveexec_b64 s[66:67], s[10:11]
	s_cbranch_execnz .LBB0_879
	s_branch .LBB0_880

.LBB0_1288:
	s_xor_b64 s[30:31], s[8:9], -1
	s_lshr_b32 s8, s12, 6
	s_and_b32 s6, s12, 4
	s_and_b32 s8, s8, 0xfffff8
	s_or_b32 s8, s8, s6
	s_lshl_b32 s6, s12, 3
	s_and_b32 s6, s6, 24
	s_bfe_u32 s9, s12, 0x30006
	s_or_b32 s6, s6, s9
	s_mov_b32 s9, 0
	s_ashr_i32 s13, s9, 31
	s_add_u32 s9, s40, s9
	s_addc_u32 s13, s41, s13
	s_add_u32 s35, s9, 0x3cb8000
	s_addc_u32 s36, s13, 0
	s_mov_b32 s9, 0
	s_ashr_i32 s13, s9, 31
	s_add_u32 s9, s40, s9
	s_addc_u32 s13, s41, s13
	s_add_u32 s37, s9, 0xe20000
	s_addc_u32 s38, s13, 0
	s_lshl_b32 s9, s12, 4
	s_lshl_b32 s8, s8, 8
	s_and_b32 s9, s9, 0x380
	v_mov_b32 v0, 0
	s_or_b32 s20, s8, s9
	v_add_u32_e32 v0, v0, v193
	s_ashr_i32 s21, s20, 31
	v_lshrrev_b32_e32 v2, 4, v0
	s_lshl_b64 s[8:9], s[20:21], 11
	v_xor_b32_e32 v1, v2, v0
	s_add_u32 s8, s35, s8
	v_lshlrev_b32_e32 v3, 3, v1
	v_lshlrev_b32_e32 v1, 7, v0
	s_addc_u32 s9, s36, s9
	s_lshl_b32 s12, s6, 18
	v_and_b32_e32 v4, 0x7ffffc00, v1
	s_add_u32 s12, s37, s12
	v_and_or_b32 v3, v3, 56, v4
	s_addc_u32 s13, s38, 0
	v_lshlrev_b32_e32 v69, 1, v3
	v_lshlrev_b32_e32 v70, 4, v0
	v_readfirstlane_b32 s21, v0
	s_and_b32 s9, s9, 0xffff
	s_and_b32 s13, s13, 0xffff
	v_add_u32_e32 v68, 0x10000, v69
	v_add_u32_e32 v66, 0x20000, v69
	v_add_u32_e32 v64, 0x30000, v69
	s_mov_b64 s[14:15], -1
	s_and_b64 vcc, exec, s[30:31]
	v_add_u32_e32 v71, 0x4000, v70
	v_add_u32_e32 v3, 0x1000, v70
	v_add_u32_e32 v4, 0x2000, v70
	v_add_u32_e32 v5, 0x3000, v70
	s_cbranch_vccz .LBB0_1290
	v_readfirstlane_b32 s14, v70
	s_mov_b32 m0, s14
	v_readfirstlane_b32 s30, v71
	v_add_u32_e32 v72, 0x1000, v70
	buffer_load_dwordx4 v69, s[8:11], 0 offen lds
	s_mov_b32 s14, s10
	s_mov_b32 s15, s11
	s_mov_b32 m0, s30
	v_readfirstlane_b32 s30, v72
	v_add_u32_e32 v6, 0x5000, v70
	buffer_load_dwordx4 v69, s[12:15], 0 offen lds
	s_mov_b32 m0, s30
	v_readfirstlane_b32 s30, v6
	v_add_u32_e32 v73, 0x2000, v70
	buffer_load_dwordx4 v68, s[8:11], 0 offen lds
	s_mov_b32 m0, s30
	v_readfirstlane_b32 s30, v73
	v_add_u32_e32 v6, 0x6000, v70
	buffer_load_dwordx4 v68, s[12:15], 0 offen lds
	s_mov_b32 m0, s30
	v_readfirstlane_b32 s30, v6
	v_add_u32_e32 v74, 0x3000, v70
	buffer_load_dwordx4 v66, s[8:11], 0 offen lds
	s_mov_b32 m0, s30
	v_readfirstlane_b32 s30, v74
	v_add_u32_e32 v6, 0x7000, v70
	buffer_load_dwordx4 v66, s[12:15], 0 offen lds
	s_mov_b32 m0, s30
	v_readfirstlane_b32 s30, v6
	buffer_load_dwordx4 v64, s[8:11], 0 offen lds
	s_mov_b32 m0, s30
	s_nop 0
	buffer_load_dwordx4 v64, s[12:15], 0 offen lds
	s_mov_b64 s[14:15], 0

.LBB0_2069:
	s_waitcnt vmcnt(0)
	s_add_i32 s87, s88, 1
	s_cmp_ge_u32 s87, s86
	s_waitcnt lgkmcnt(0)
	s_barrier
	s_cbranch_scc1 .LBB0_2115
	s_lshl_b32 s90, s87, 6
	s_add_u32 s34, s56, s90
	s_addc_u32 s35, s57, 0
	s_bitcmp1_b32 s87, 0
	s_cselect_b32 s89, 0x5800, 0
	s_cmp_lg_u32 s87, 1
	s_cbranch_scc1 .Lhwat1_fast
	s_and_saveexec_b64 s[66:67], s[6:7]
	s_cbranch_execnz .LBB0_2074
	s_or_b64 exec, exec, s[66:67]
	s_and_saveexec_b64 s[66:67], s[8:9]
	s_cbranch_execnz .LBB0_2083

.LBB0_2080:
	s_andn2_saveexec_b64 s[68:69], s[68:69]
	v_lshlrev_b64 v[64:65], 10, v[66:67]
	v_lshl_add_u64 v[64:65], v[156:157], 0, v[64:65]
	s_or_b64 exec, exec, s[68:69]
	v_mov_b32_e32 v152, v64
	v_mov_b32_e32 v153, v65
	s_andn2_b64 vcc, s[14:15], s[16:17]
	v_mov_b32_e32 v154, 0x10000
	v_mov_b32_e32 v67, 0x1000
	v_cndmask_b32_e32 v154, v154, v67, vcc
	v_readfirstlane_b32 s98, v191
	v_add_u32_e32 v66, s89, v191
	s_nop 0
	v_readfirstlane_b32 s30, v66
	s_mov_b32 m0, s30
	s_nop 0
	global_load_lds_dwordx4 v[64:65], off
	s_or_b64 exec, exec, s[66:67]
	s_and_saveexec_b64 s[66:67], s[8:9]
	s_cbranch_execz .LBB0_2072

.LBB0_2089:
	s_andn2_saveexec_b64 s[68:69], s[68:69]
	v_lshlrev_b64 v[64:65], 10, v[66:67]
	v_lshl_add_u64 v[64:65], v[162:163], 0, v[64:65]
	s_or_b64 exec, exec, s[68:69]
	v_mov_b32_e32 v158, v64
	v_mov_b32_e32 v159, v65
	s_andn2_b64 vcc, s[18:19], s[20:21]
	v_mov_b32_e32 v160, 0x10000
	v_mov_b32_e32 v67, 0x1000
	v_cndmask_b32_e32 v160, v160, v67, vcc
	v_readfirstlane_b32 s99, v196
	v_add_u32_e32 v66, s89, v196
	s_nop 0
	v_readfirstlane_b32 s30, v66
	s_mov_b32 m0, s30
	s_nop 0
	global_load_lds_dwordx4 v[64:65], off
	s_or_b64 exec, exec, s[66:67]
	s_and_saveexec_b64 s[66:67], s[10:11]
	s_cbranch_execz .LBB0_2073

.LBB0_2098:
	s_andn2_saveexec_b64 s[68:69], s[68:69]
	v_lshlrev_b64 v[64:65], 10, v[66:67]
	v_lshl_add_u64 v[64:65], v[168:169], 0, v[64:65]
	s_or_b64 exec, exec, s[68:69]
	v_mov_b32_e32 v164, v64
	v_mov_b32_e32 v165, v65
	s_andn2_b64 vcc, s[22:23], s[24:25]
	v_mov_b32_e32 v166, 0x10000
	v_mov_b32_e32 v67, 0x1000
	v_cndmask_b32_e32 v166, v166, v67, vcc
	v_readfirstlane_b32 s100, v189
	v_add_u32_e32 v66, s89, v189
	s_nop 0
	v_readfirstlane_b32 s30, v66
	s_mov_b32 m0, s30
	s_nop 0
	global_load_lds_dwordx4 v[64:65], off
	s_or_b64 exec, exec, s[66:67]
	s_and_saveexec_b64 s[66:67], s[12:13]
	s_cbranch_execz .LBB0_2110

.LBB0_2107:
	s_andn2_saveexec_b64 s[34:35], s[34:35]
	v_lshlrev_b64 v[64:65], 10, v[66:67]
	v_lshl_add_u64 v[64:65], v[174:175], 0, v[64:65]
	s_or_b64 exec, exec, s[34:35]
	v_mov_b32_e32 v170, v64
	v_mov_b32_e32 v171, v65
	s_andn2_b64 vcc, s[26:27], s[28:29]
	v_mov_b32_e32 v172, 0x10000
	v_mov_b32_e32 v67, 0x1000
	v_cndmask_b32_e32 v172, v172, v67, vcc
	v_readfirstlane_b32 s101, v197
	v_add_u32_e32 v66, s89, v197
	s_nop 0
	v_readfirstlane_b32 s30, v66
	s_mov_b32 m0, s30
	s_nop 0
	global_load_lds_dwordx4 v[64:65], off

.LBB0_2113:
	v_add_u32_e32 v64, s89, v189
	v_add_u32_e32 v66, 0x3400, v64
	v_lshl_add_u64 v[64:65], v[148:149], 1, s[34:35]
	v_readfirstlane_b32 s30, v66
	v_lshl_add_u64 v[64:65], v[184:185], 1, v[64:65]
	v_mov_b32_e32 v148, v64
	v_mov_b32_e32 v149, v65
	s_mov_b32 m0, s30
	s_nop 0
	global_load_lds_dwordx4 v[64:65], off

.Lhwat1_fast:
	s_and_saveexec_b64 s[66:67], s[6:7]
	s_cbranch_execz .Lhwat1_k0
	s_add_u32 m0, s98, s89
	v_add_co_u32_e32 v152, vcc, v152, v154
	s_nop 1
	v_addc_co_u32_e32 v153, vcc, 0, v153, vcc
	global_load_lds_dwordx4 v[152:153], off
.Lhwat1_k0:
	s_or_b64 exec, exec, s[66:67]
	s_and_saveexec_b64 s[66:67], s[8:9]
	s_cbranch_execz .Lhwat1_k1
	s_add_u32 m0, s99, s89
	v_add_co_u32_e32 v158, vcc, v158, v160
	s_nop 1
	v_addc_co_u32_e32 v159, vcc, 0, v159, vcc
	global_load_lds_dwordx4 v[158:159], off
.Lhwat1_k1:
	s_or_b64 exec, exec, s[66:67]
	s_and_saveexec_b64 s[66:67], s[10:11]
	s_cbranch_execz .Lhwat1_k2
	s_add_u32 m0, s100, s89
	v_add_co_u32_e32 v164, vcc, v164, v166
	s_nop 1
	v_addc_co_u32_e32 v165, vcc, 0, v165, vcc
	global_load_lds_dwordx4 v[164:165], off
.Lhwat1_k2:
	s_or_b64 exec, exec, s[66:67]
	s_and_saveexec_b64 s[66:67], s[12:13]
	s_cbranch_execz .Lhwat1_k3
	s_add_u32 m0, s101, s89
	v_add_co_u32_e32 v170, vcc, v170, v172
	s_nop 1
	v_addc_co_u32_e32 v171, vcc, 0, v171, vcc
	global_load_lds_dwordx4 v[170:171], off
.Lhwat1_k3:
	s_or_b64 exec, exec, s[66:67]
	s_and_saveexec_b64 s[66:67], s[8:9]
	s_cbranch_execz .Lhwat1_v0
	s_add_u32 s30, s98, s89
	s_add_u32 m0, s30, 0x3400
	v_add_co_u32_e32 v176, vcc, 0x80, v176
	s_nop 1
	v_addc_co_u32_e32 v177, vcc, 0, v177, vcc
	global_load_lds_dwordx4 v[176:177], off
.Lhwat1_v0:
	s_or_b64 exec, exec, s[66:67]
	s_and_saveexec_b64 s[66:67], s[10:11]
	s_cbranch_execz .Lhwat1_v1
	s_add_u32 s30, s99, s89
	s_add_u32 m0, s30, 0x3400
	v_add_co_u32_e32 v180, vcc, 0x80, v180
	s_nop 1
	v_addc_co_u32_e32 v181, vcc, 0, v181, vcc
	global_load_lds_dwordx4 v[180:181], off
.Lhwat1_v1:
	s_or_b64 exec, exec, s[66:67]
	s_and_saveexec_b64 s[66:67], s[12:13]
	s_cbranch_execz .Lhwat1_v2
	s_add_u32 s30, s100, s89
	s_add_u32 m0, s30, 0x3400
	v_add_co_u32_e32 v148, vcc, 0x80, v148
	s_nop 1
	v_addc_co_u32_e32 v149, vcc, 0, v149, vcc
	global_load_lds_dwordx4 v[148:149], off

.LBB0_2125:
	v_add_u32_e32 v64, s89, v191
	v_add_u32_e32 v66, 0x3400, v64
	v_lshl_add_u64 v[64:65], v[176:177], 1, s[34:35]
	v_readfirstlane_b32 s30, v66
	v_lshl_add_u64 v[64:65], v[178:179], 1, v[64:65]
	v_mov_b32_e32 v176, v64
	v_mov_b32_e32 v177, v65
	s_mov_b32 m0, s30
	s_nop 0
	global_load_lds_dwordx4 v[64:65], off
	s_or_b64 exec, exec, s[66:67]
	s_and_saveexec_b64 s[66:67], s[10:11]
	s_cbranch_execz .LBB0_2112
.LBB0_2126:
	v_add_u32_e32 v64, s89, v196
	v_add_u32_e32 v66, 0x3400, v64
	v_lshl_add_u64 v[64:65], v[180:181], 1, s[34:35]
	v_readfirstlane_b32 s30, v66
	v_lshl_add_u64 v[64:65], v[182:183], 1, v[64:65]
	v_mov_b32_e32 v180, v64
	v_mov_b32_e32 v181, v65
	s_mov_b32 m0, s30
	s_nop 0
	global_load_lds_dwordx4 v[64:65], off
	s_or_b64 exec, exec, s[66:67]
	s_and_saveexec_b64 s[66:67], s[12:13]
	s_cbranch_execnz .LBB0_2113
	s_branch .LBB0_2114

	.amdhsa_kernel _Z14fwd_megakernel6Params
		.amdhsa_group_segment_fixed_size 65536
		.amdhsa_private_segment_fixed_size 0
		.amdhsa_kernarg_size 504
		.amdhsa_user_sgpr_count 2
		.amdhsa_user_sgpr_dispatch_ptr 0
		.amdhsa_user_sgpr_queue_ptr 0
		.amdhsa_user_sgpr_kernarg_segment_ptr 1
		.amdhsa_user_sgpr_dispatch_id 0
		.amdhsa_user_sgpr_kernarg_preload_length 0
		.amdhsa_user_sgpr_kernarg_preload_offset 0
		.amdhsa_user_sgpr_private_segment_size 0
		.amdhsa_uses_dynamic_stack 0
		.amdhsa_enable_private_segment 0
		.amdhsa_system_sgpr_workgroup_id_x 1
		.amdhsa_system_sgpr_workgroup_id_y 0
		.amdhsa_system_sgpr_workgroup_id_z 0
		.amdhsa_system_sgpr_workgroup_info 0
		.amdhsa_system_vgpr_workitem_id 2
		.amdhsa_next_free_vgpr 245
		.amdhsa_next_free_sgpr 102
		.amdhsa_accum_offset 248
		.amdhsa_reserve_vcc 1
		.amdhsa_float_round_mode_32 0
		.amdhsa_float_round_mode_16_64 0
		.amdhsa_float_denorm_mode_32 3
		.amdhsa_float_denorm_mode_16_64 3
		.amdhsa_dx10_clamp 1
		.amdhsa_ieee_mode 1
		.amdhsa_fp16_overflow 0
		.amdhsa_tg_split 0
		.amdhsa_exception_fp_ieee_invalid_op 0
		.amdhsa_exception_fp_denorm_src 0
		.amdhsa_exception_fp_ieee_div_zero 0
		.amdhsa_exception_fp_ieee_overflow 0
		.amdhsa_exception_fp_ieee_underflow 0
		.amdhsa_exception_fp_ieee_inexact 0
		.amdhsa_exception_int_div_zero 0
	.end_amdhsa_kernel
